# FoX attention epilogue: in-register 4x4 DPP transpose + dwordx2 stores instead of the 32-step ds_bpermute chain
# baseline (speedup 1.0000x reference)
.LBB0_390:
	v_cmp_gt_u32_e32 vcc, 32, v135
	s_and_saveexec_b64 s[0:1], vcc
	ds_write_b32 v112, v111 offset:49152
	s_or_b64 exec, exec, s[0:1]
	s_waitcnt lgkmcnt(0)
	ds_read_b128 v[160:163], v110 offset:49152
	ds_read_b128 v[164:167], v110 offset:49184
	ds_read_b128 v[168:171], v110 offset:49216
	ds_read_b128 v[172:175], v110 offset:49248
	s_ashr_i32 s29, s28, 31
	s_lshl_b64 s[0:1], s[28:29], 11
	s_add_u32 s0, s30, s0
	s_addc_u32 s1, s31, s1
	s_mov_b32 s98, 0x33333333
	s_mov_b32 s99, 0x33333333
	s_mov_b32 s100, 0xaaaaaaaa
	s_mov_b32 s101, 0xaaaaaaaa
	s_mov_b64 vcc, 0x4000
	v_and_b32_e32 v225, 3, v135
	v_add_u32_e32 v225, v225, v132
	v_and_b32_e32 v226, 28, v134
	v_lshlrev_b32_e32 v225, 11, v225
	v_lshl_add_u32 v216, v226, 1, v225
	v_mov_b32_e32 v217, 0
	v_mov_b32_e32 v225, 0x5040100
	v_mov_b32_e32 v226, 0x3020706
	v_lshl_add_u64 v[216:217], v[216:217], 0, s[0:1]
	v_cndmask_b32_e64 v224, v225, v226, s[100:101]
	v_lshl_add_u64 v[218:219], v[216:217], 0, vcc
	v_lshl_add_u64 v[220:221], v[218:219], 0, vcc
	v_lshl_add_u64 v[222:223], v[220:221], 0, vcc
	s_waitcnt lgkmcnt(0)
	v_rcp_f32_e32 v160, v160
	v_rcp_f32_e32 v161, v161
	v_rcp_f32_e32 v162, v162
	v_rcp_f32_e32 v163, v163
	v_rcp_f32_e32 v164, v164
	v_rcp_f32_e32 v165, v165
	v_rcp_f32_e32 v166, v166
	v_rcp_f32_e32 v167, v167
	v_rcp_f32_e32 v168, v168
	v_rcp_f32_e32 v169, v169
	v_rcp_f32_e32 v170, v170
	v_rcp_f32_e32 v171, v171
	v_rcp_f32_e32 v172, v172
	v_rcp_f32_e32 v173, v173
	v_rcp_f32_e32 v174, v174
	v_rcp_f32_e32 v175, v175
	s_nop 0
	v_mul_f32_e32 v20, v20, v160
	v_mul_f32_e32 v21, v21, v161
	v_mul_f32_e32 v22, v22, v162
	v_mul_f32_e32 v23, v23, v163
	v_mul_f32_e32 v24, v24, v164
	v_mul_f32_e32 v25, v25, v165
	v_mul_f32_e32 v26, v26, v166
	v_mul_f32_e32 v27, v27, v167
	v_mul_f32_e32 v28, v28, v168
	v_mul_f32_e32 v29, v29, v169
	v_mul_f32_e32 v30, v30, v170
	v_mul_f32_e32 v31, v31, v171
	v_mul_f32_e32 v32, v32, v172
	v_mul_f32_e32 v33, v33, v173
	v_mul_f32_e32 v34, v34, v174
	v_mul_f32_e32 v35, v35, v175
	v_cvt_pk_bf16_f32 v20, v20, v21
	v_cvt_pk_bf16_f32 v22, v22, v23
	v_cvt_pk_bf16_f32 v24, v24, v25
	v_cvt_pk_bf16_f32 v26, v26, v27
	v_cvt_pk_bf16_f32 v28, v28, v29
	v_cvt_pk_bf16_f32 v30, v30, v31
	v_cvt_pk_bf16_f32 v32, v32, v33
	v_cvt_pk_bf16_f32 v34, v34, v35
	s_nop 1
	v_mov_b32_dpp v21, v20 quad_perm:[1,0,3,2] row_mask:0xf bank_mask:0xf
	v_mov_b32_dpp v23, v22 quad_perm:[1,0,3,2] row_mask:0xf bank_mask:0xf
	v_mov_b32_dpp v25, v24 quad_perm:[1,0,3,2] row_mask:0xf bank_mask:0xf
	v_mov_b32_dpp v27, v26 quad_perm:[1,0,3,2] row_mask:0xf bank_mask:0xf
	v_mov_b32_dpp v29, v28 quad_perm:[1,0,3,2] row_mask:0xf bank_mask:0xf
	v_mov_b32_dpp v31, v30 quad_perm:[1,0,3,2] row_mask:0xf bank_mask:0xf
	v_mov_b32_dpp v33, v32 quad_perm:[1,0,3,2] row_mask:0xf bank_mask:0xf
	v_mov_b32_dpp v35, v34 quad_perm:[1,0,3,2] row_mask:0xf bank_mask:0xf
	v_perm_b32 v20, v21, v20, v224
	v_perm_b32 v22, v23, v22, v224
	v_perm_b32 v24, v25, v24, v224
	v_perm_b32 v26, v27, v26, v224
	v_perm_b32 v28, v29, v28, v224
	v_perm_b32 v30, v31, v30, v224
	v_perm_b32 v32, v33, v32, v224
	v_perm_b32 v34, v35, v34, v224
	v_cndmask_b32_e64 v21, v20, v22, s[98:99]
	v_cndmask_b32_e64 v25, v24, v26, s[98:99]
	v_cndmask_b32_e64 v29, v28, v30, s[98:99]
	v_cndmask_b32_e64 v33, v32, v34, s[98:99]
	s_nop 1
	v_mov_b32_dpp v23, v21 quad_perm:[2,3,0,1] row_mask:0xf bank_mask:0xf
	v_mov_b32_dpp v27, v25 quad_perm:[2,3,0,1] row_mask:0xf bank_mask:0xf
	v_mov_b32_dpp v31, v29 quad_perm:[2,3,0,1] row_mask:0xf bank_mask:0xf
	v_mov_b32_dpp v35, v33 quad_perm:[2,3,0,1] row_mask:0xf bank_mask:0xf
	v_cndmask_b32_e64 v21, v22, v23, s[98:99]
	v_cndmask_b32_e64 v20, v23, v20, s[98:99]
	v_cndmask_b32_e64 v25, v26, v27, s[98:99]
	v_cndmask_b32_e64 v24, v27, v24, s[98:99]
	v_cndmask_b32_e64 v29, v30, v31, s[98:99]
	v_cndmask_b32_e64 v28, v31, v28, s[98:99]
	v_cndmask_b32_e64 v33, v34, v35, s[98:99]
	v_cndmask_b32_e64 v32, v35, v32, s[98:99]
	global_store_dwordx2 v[216:217], v[20:21], off
	global_store_dwordx2 v[218:219], v[24:25], off
	global_store_dwordx2 v[220:221], v[28:29], off
	global_store_dwordx2 v[222:223], v[32:33], off
	v_mul_f32_e32 v2, v2, v160
	v_mul_f32_e32 v3, v3, v161
	v_mul_f32_e32 v4, v4, v162
	v_mul_f32_e32 v5, v5, v163
	v_mul_f32_e32 v6, v6, v164
	v_mul_f32_e32 v7, v7, v165
	v_mul_f32_e32 v8, v8, v166
	v_mul_f32_e32 v9, v9, v167
	v_mul_f32_e32 v10, v10, v168
	v_mul_f32_e32 v11, v11, v169
	v_mul_f32_e32 v12, v12, v170
	v_mul_f32_e32 v13, v13, v171
	v_mul_f32_e32 v14, v14, v172
	v_mul_f32_e32 v15, v15, v173
	v_mul_f32_e32 v16, v16, v174
	v_mul_f32_e32 v17, v17, v175
	v_cvt_pk_bf16_f32 v2, v2, v3
	v_cvt_pk_bf16_f32 v4, v4, v5
	v_cvt_pk_bf16_f32 v6, v6, v7
	v_cvt_pk_bf16_f32 v8, v8, v9
	v_cvt_pk_bf16_f32 v10, v10, v11
	v_cvt_pk_bf16_f32 v12, v12, v13
	v_cvt_pk_bf16_f32 v14, v14, v15
	v_cvt_pk_bf16_f32 v16, v16, v17
	s_nop 1
	v_mov_b32_dpp v3, v2 quad_perm:[1,0,3,2] row_mask:0xf bank_mask:0xf
	v_mov_b32_dpp v5, v4 quad_perm:[1,0,3,2] row_mask:0xf bank_mask:0xf
	v_mov_b32_dpp v7, v6 quad_perm:[1,0,3,2] row_mask:0xf bank_mask:0xf
	v_mov_b32_dpp v9, v8 quad_perm:[1,0,3,2] row_mask:0xf bank_mask:0xf
	v_mov_b32_dpp v11, v10 quad_perm:[1,0,3,2] row_mask:0xf bank_mask:0xf
	v_mov_b32_dpp v13, v12 quad_perm:[1,0,3,2] row_mask:0xf bank_mask:0xf
	v_mov_b32_dpp v15, v14 quad_perm:[1,0,3,2] row_mask:0xf bank_mask:0xf
	v_mov_b32_dpp v17, v16 quad_perm:[1,0,3,2] row_mask:0xf bank_mask:0xf
	v_perm_b32 v2, v3, v2, v224
	v_perm_b32 v4, v5, v4, v224
	v_perm_b32 v6, v7, v6, v224
	v_perm_b32 v8, v9, v8, v224
	v_perm_b32 v10, v11, v10, v224
	v_perm_b32 v12, v13, v12, v224
	v_perm_b32 v14, v15, v14, v224
	v_perm_b32 v16, v17, v16, v224
	v_cndmask_b32_e64 v3, v2, v4, s[98:99]
	v_cndmask_b32_e64 v7, v6, v8, s[98:99]
	v_cndmask_b32_e64 v11, v10, v12, s[98:99]
	v_cndmask_b32_e64 v15, v14, v16, s[98:99]
	s_nop 1
	v_mov_b32_dpp v5, v3 quad_perm:[2,3,0,1] row_mask:0xf bank_mask:0xf
	v_mov_b32_dpp v9, v7 quad_perm:[2,3,0,1] row_mask:0xf bank_mask:0xf
	v_mov_b32_dpp v13, v11 quad_perm:[2,3,0,1] row_mask:0xf bank_mask:0xf
	v_mov_b32_dpp v17, v15 quad_perm:[2,3,0,1] row_mask:0xf bank_mask:0xf
	v_cndmask_b32_e64 v3, v4, v5, s[98:99]
	v_cndmask_b32_e64 v2, v5, v2, s[98:99]
	v_cndmask_b32_e64 v7, v8, v9, s[98:99]
	v_cndmask_b32_e64 v6, v9, v6, s[98:99]
	v_cndmask_b32_e64 v11, v12, v13, s[98:99]
	v_cndmask_b32_e64 v10, v13, v10, s[98:99]
	v_cndmask_b32_e64 v15, v16, v17, s[98:99]
	v_cndmask_b32_e64 v14, v17, v14, s[98:99]
	global_store_dwordx2 v[216:217], v[2:3], off offset:64
	global_store_dwordx2 v[218:219], v[6:7], off offset:64
	global_store_dwordx2 v[220:221], v[10:11], off offset:64
	global_store_dwordx2 v[222:223], v[14:15], off offset:64
	s_branch .LBB0_324
